# in_proj units re-paired per workgroup: (Q,K) and (V,U) instead of (Q,V) and (K,U) by swapping two bits of the column-tile index
# baseline (speedup 1.0000x reference)
.Lxbn1_end:
.LBB0_186:
	s_or_b64 exec, exec, s[4:5]
	s_mov_b64 s[16:17], s[0:1]
	s_waitcnt lgkmcnt(0)
	s_barrier
	s_load_dwordx2 s[18:19], s[16:17], 0xe8
	v_mov_b32_e32 v14, v170
	s_cmpk_lt_i32 s2, 0x180
	s_cselect_b64 s[4:5], -1, 0
	s_cmpk_gt_i32 s2, 0x17f
	v_readfirstlane_b32 s45, v14
	s_cbranch_scc1 .LBB0_188
	s_ashr_i32 s3, s2, 31
	s_lshr_b32 s3, s3, 29
	s_add_i32 s3, s2, s3
	s_ashr_i32 s6, s3, 3
	s_and_b32 s3, s3, -8
	s_sub_i32 s3, s2, s3
	s_lshr_b32 s7, s3, 31
	s_or_b32 s7, s7, 48
	s_mul_i32 s3, s7, s3
	s_add_i32 s3, s3, s6
	s_ashr_i32 s6, s3, 31
	s_lshr_b32 s6, s6, 26
	s_add_i32 s6, s3, s6
	s_ashr_i32 s6, s6, 6
	s_lshl_b32 s8, s6, 3
	s_sub_i32 s7, 48, s8
	s_lshl_b32 s6, s6, 6
	s_min_u32 s9, s7, 8
	s_sub_i32 s3, s3, s6
	s_sext_i32_i8 s6, s3
	v_cvt_f32_ubyte0_e32 v1, s9
	v_cvt_f32_i32_e32 v0, s6
	v_rcp_iflag_f32_e32 v2, v1
	s_ashr_i32 s6, s6, 30
	s_or_b32 s10, s6, 1
	v_mul_f32_e32 v2, v0, v2
	v_trunc_f32_e32 v2, v2
	v_fma_f32 v0, -v2, v1, v0
	v_cvt_i32_f32_e32 v2, v2
	v_cmp_ge_f32_e64 s[6:7], |v0|, v1
	s_and_b64 s[6:7], s[6:7], exec
	s_cselect_b32 s6, s10, 0
	v_readfirstlane_b32 s7, v2
	s_add_i32 s6, s7, s6
	s_sext_i32_i8 s12, s6
	s_mul_i32 s6, s6, s9
	s_sub_i32 s3, s3, s6
	s_sext_i32_i8 s3, s3
	s_add_i32 s10, s8, s3
	s_lshr_b32 s3, s12, 1
	s_xor_b32 s3, s3, s12
	s_and_b32 s3, s3, 2
	s_mul_i32 s3, s3, 3
	s_xor_b32 s12, s12, s3

.LBB0_193:
	s_add_i32 s79, s79, 1
	s_mul_i32 s6, s79, s69
	s_mul_hi_u32 s7, s79, s70
	s_add_i32 s7, s7, s6
	s_mul_i32 s6, s79, s70
	s_add_u32 s36, s6, s2
	s_addc_u32 s37, s7, s3
	v_cmp_gt_i64_e64 s[6:7], s[36:37], v[142:143]
	s_and_b64 vcc, exec, s[6:7]
	s_cbranch_vccnz .LBB0_195
	s_ashr_i32 s11, s36, 31
	s_lshr_b32 s11, s11, 29
	s_add_i32 s11, s36, s11
	s_ashr_i32 s13, s11, 3
	s_and_b32 s11, s11, -8
	s_sub_i32 s11, s36, s11
	s_lshr_b32 s30, s11, 31
	s_or_b32 s30, s30, 48
	s_mul_i32 s11, s30, s11
	s_add_i32 s11, s11, s13
	s_ashr_i32 s13, s11, 31
	s_lshr_b32 s13, s13, 26
	s_add_i32 s13, s11, s13
	s_ashr_i32 s30, s13, 6
	s_lshl_b32 s31, s30, 3
	s_sub_i32 s30, 48, s31
	s_min_i32 s33, s30, 8
	s_abs_i32 s30, s33
	v_cvt_f32_u32_e32 v0, s30
	s_sub_i32 s35, 0, s30
	s_andn2_b32 s13, s13, 63
	s_sub_i32 s11, s11, s13
	v_rcp_iflag_f32_e32 v0, v0
	s_abs_i32 s13, s11
	s_xor_b32 s34, s11, s33
	s_ashr_i32 s34, s34, 31
	v_mul_f32_e32 v0, 0x4f7ffffe, v0
	v_cvt_u32_f32_e32 v0, v0
	s_nop 0
	v_readfirstlane_b32 s40, v0
	s_mul_i32 s35, s35, s40
	s_mul_hi_u32 s35, s40, s35
	s_add_i32 s40, s40, s35
	s_mul_hi_u32 s35, s13, s40
	s_mul_i32 s40, s35, s30
	s_sub_i32 s13, s13, s40
	s_add_i32 s41, s35, 1
	s_sub_i32 s40, s13, s30
	s_cmp_ge_u32 s13, s30
	s_cselect_b32 s35, s41, s35
	s_cselect_b32 s13, s40, s13
	s_add_i32 s40, s35, 1
	s_cmp_ge_u32 s13, s30
	s_cselect_b32 s13, s40, s35
	s_xor_b32 s13, s13, s34
	s_sub_i32 s30, s13, s34
	s_mul_i32 s13, s30, s33
	s_sub_i32 s11, s11, s13
	s_add_i32 s34, s11, s31
	s_lshr_b32 s11, s30, 1
	s_xor_b32 s11, s11, s30
	s_and_b32 s11, s11, 2
	s_mul_i32 s11, s11, 3
	s_xor_b32 s30, s30, s11
